# best + hand-scheduled SwiGLU epilogue (same arithmetic, interleaved chains, scalar f32 ops) in the 4 gate-up GEMMs
# speedup vs baseline: 1.0034x; 1.0034x over previous
.LBB0_76:
	s_movk_i32 s84, 0x1600
	s_mov_b64 s[88:89], 0x16000
	s_mov_b64 s[90:91], 0x6e000
	v_lshl_add_u32 v178, s48, 12, v168
	ds_read_b128 v[180:183], v178 offset:0
	ds_read_b128 v[184:187], v178 offset:256
	ds_read_b128 v[188:191], v178 offset:512
	ds_read_b128 v[192:195], v178 offset:768
	ds_read_b128 v[196:199], v178 offset:2048
	ds_read_b128 v[200:203], v178 offset:2304
	ds_read_b128 v[204:207], v178 offset:2560
	ds_read_b128 v[208:211], v178 offset:2816
	v_lshl_add_u32 v218, s28, 8, v166
	v_lshl_or_b32 v222, s30, 7, v169
	v_mov_b32_e32 v223, 0
	v_lshlrev_b32_e32 v222, 1, v222
	v_mad_u64_u32 v[220:221], s[82:83], v218, s84, v[142:143]
	v_lshl_add_u64 v[220:221], v[222:223], 0, v[220:221]
	s_waitcnt lgkmcnt(0)
	v_add_f32_e32 v180, v180, v181
	v_add_f32_e32 v184, v184, v185
	v_add_f32_e32 v188, v188, v189
	v_add_f32_e32 v192, v192, v193
	v_add_f32_e32 v196, v196, v197
	v_add_f32_e32 v200, v200, v201
	v_add_f32_e32 v204, v204, v205
	v_add_f32_e32 v208, v208, v209
	v_add_f32_e32 v182, v182, v183
	v_add_f32_e32 v186, v186, v187
	v_add_f32_e32 v190, v190, v191
	v_add_f32_e32 v194, v194, v195
	v_add_f32_e32 v198, v198, v199
	v_add_f32_e32 v202, v202, v203
	v_add_f32_e32 v206, v206, v207
	v_add_f32_e32 v210, v210, v211
	v_add_f32_e32 v180, v180, v182
	v_add_f32_e32 v184, v184, v186
	v_add_f32_e32 v188, v188, v190
	v_add_f32_e32 v192, v192, v194
	v_add_f32_e32 v196, v196, v198
	v_add_f32_e32 v200, v200, v202
	v_add_f32_e32 v204, v204, v206
	v_add_f32_e32 v208, v208, v210
	v_fmamk_f32 v180, v180, 0x3a800000, v171
	v_fmamk_f32 v184, v184, 0x3a800000, v171
	v_fmamk_f32 v188, v188, 0x3a800000, v171
	v_fmamk_f32 v192, v192, 0x3a800000, v171
	v_fmamk_f32 v196, v196, 0x3a800000, v171
	v_fmamk_f32 v200, v200, 0x3a800000, v171
	v_fmamk_f32 v204, v204, 0x3a800000, v171
	v_fmamk_f32 v208, v208, 0x3a800000, v171
	v_rsq_f32_e32 v180, v180
	v_rsq_f32_e32 v184, v184
	v_rsq_f32_e32 v188, v188
	v_rsq_f32_e32 v192, v192
	v_rsq_f32_e32 v196, v196
	v_rsq_f32_e32 v200, v200
	v_rsq_f32_e32 v204, v204
	v_rsq_f32_e32 v208, v208
	v_mul_f32_e32 v232, 0xbfb8aa3b, v180
	v_mul_f32_e32 v234, 0xbfb8aa3b, v184
	v_mul_f32_e32 v236, 0xbfb8aa3b, v188
	v_mul_f32_e32 v238, 0xbfb8aa3b, v192
	v_mul_f32_e32 v240, 0xbfb8aa3b, v196
	v_mul_f32_e32 v242, 0xbfb8aa3b, v200
	v_mul_f32_e32 v244, 0xbfb8aa3b, v204
	v_mul_f32_e32 v246, 0xbfb8aa3b, v208
	v_mul_f32_e32 v233, v180, v180
	v_mul_f32_e32 v235, v184, v184
	v_mul_f32_e32 v237, v188, v188
	v_mul_f32_e32 v239, v192, v192
	v_mul_f32_e32 v241, v196, v196
	v_mul_f32_e32 v243, v200, v200
	v_mul_f32_e32 v245, v204, v204
	v_mul_f32_e32 v247, v208, v208
	v_mul_f32_e32 v224, v124, v232
	v_mul_f32_e32 v225, v125, v232
	v_mul_f32_e32 v226, v126, v232
	v_mul_f32_e32 v227, v127, v232
	v_mul_f32_e32 v228, v116, v232
	v_mul_f32_e32 v229, v117, v232
	v_mul_f32_e32 v230, v118, v232
	v_mul_f32_e32 v231, v119, v232
	v_mul_f32_e32 v120, v124, v120
	v_mul_f32_e32 v121, v125, v121
	v_mul_f32_e32 v122, v126, v122
	v_mul_f32_e32 v123, v127, v123
	v_mul_f32_e32 v112, v116, v112
	v_mul_f32_e32 v113, v117, v113
	v_mul_f32_e32 v114, v118, v114
	v_mul_f32_e32 v115, v119, v115
	v_exp_f32_e32 v224, v224
	v_exp_f32_e32 v225, v225
	v_exp_f32_e32 v226, v226
	v_exp_f32_e32 v227, v227
	v_exp_f32_e32 v228, v228
	v_exp_f32_e32 v229, v229
	v_exp_f32_e32 v230, v230
	v_exp_f32_e32 v231, v231
	v_mul_f32_e32 v120, v120, v233
	v_mul_f32_e32 v121, v121, v233
	v_mul_f32_e32 v122, v122, v233
	v_mul_f32_e32 v123, v123, v233
	v_mul_f32_e32 v112, v112, v233
	v_mul_f32_e32 v113, v113, v233
	v_mul_f32_e32 v114, v114, v233
	v_mul_f32_e32 v115, v115, v233
	v_add_f32_e32 v224, 1.0, v224
	v_add_f32_e32 v225, 1.0, v225
	v_add_f32_e32 v226, 1.0, v226
	v_add_f32_e32 v227, 1.0, v227
	v_add_f32_e32 v228, 1.0, v228
	v_add_f32_e32 v229, 1.0, v229
	v_add_f32_e32 v230, 1.0, v230
	v_add_f32_e32 v231, 1.0, v231
	v_rcp_f32_e32 v224, v224
	v_rcp_f32_e32 v225, v225
	v_rcp_f32_e32 v226, v226
	v_rcp_f32_e32 v227, v227
	v_rcp_f32_e32 v228, v228
	v_rcp_f32_e32 v229, v229
	v_rcp_f32_e32 v230, v230
	v_rcp_f32_e32 v231, v231
	v_mul_f32_e32 v120, v120, v224
	v_mul_f32_e32 v121, v121, v225
	v_mul_f32_e32 v122, v122, v226
	v_mul_f32_e32 v123, v123, v227
	v_mul_f32_e32 v112, v112, v228
	v_mul_f32_e32 v113, v113, v229
	v_mul_f32_e32 v114, v114, v230
	v_mul_f32_e32 v115, v115, v231
	v_cvt_pk_bf16_f32 v180, v120, v121
	v_cvt_pk_bf16_f32 v181, v122, v123
	v_cvt_pk_bf16_f32 v182, v112, v113
	v_cvt_pk_bf16_f32 v183, v114, v115
	global_store_dwordx4 v[220:221], v[180:183], off
	v_lshl_add_u64 v[220:221], v[220:221], 0, s[88:89]
	v_mul_f32_e32 v224, v108, v234
	v_mul_f32_e32 v225, v109, v234
	v_mul_f32_e32 v226, v110, v234
	v_mul_f32_e32 v227, v111, v234
	v_mul_f32_e32 v228, v100, v234
	v_mul_f32_e32 v229, v101, v234
	v_mul_f32_e32 v230, v102, v234
	v_mul_f32_e32 v231, v103, v234
	v_mul_f32_e32 v104, v108, v104
	v_mul_f32_e32 v105, v109, v105
	v_mul_f32_e32 v106, v110, v106
	v_mul_f32_e32 v107, v111, v107
	v_mul_f32_e32 v96, v100, v96
	v_mul_f32_e32 v97, v101, v97
	v_mul_f32_e32 v98, v102, v98
	v_mul_f32_e32 v99, v103, v99
	v_exp_f32_e32 v224, v224
	v_exp_f32_e32 v225, v225
	v_exp_f32_e32 v226, v226
	v_exp_f32_e32 v227, v227
	v_exp_f32_e32 v228, v228
	v_exp_f32_e32 v229, v229
	v_exp_f32_e32 v230, v230
	v_exp_f32_e32 v231, v231
	v_mul_f32_e32 v104, v104, v235
	v_mul_f32_e32 v105, v105, v235
	v_mul_f32_e32 v106, v106, v235
	v_mul_f32_e32 v107, v107, v235
	v_mul_f32_e32 v96, v96, v235
	v_mul_f32_e32 v97, v97, v235
	v_mul_f32_e32 v98, v98, v235
	v_mul_f32_e32 v99, v99, v235
	v_add_f32_e32 v224, 1.0, v224
	v_add_f32_e32 v225, 1.0, v225
	v_add_f32_e32 v226, 1.0, v226
	v_add_f32_e32 v227, 1.0, v227
	v_add_f32_e32 v228, 1.0, v228
	v_add_f32_e32 v229, 1.0, v229
	v_add_f32_e32 v230, 1.0, v230
	v_add_f32_e32 v231, 1.0, v231
	v_rcp_f32_e32 v224, v224
	v_rcp_f32_e32 v225, v225
	v_rcp_f32_e32 v226, v226
	v_rcp_f32_e32 v227, v227
	v_rcp_f32_e32 v228, v228
	v_rcp_f32_e32 v229, v229
	v_rcp_f32_e32 v230, v230
	v_rcp_f32_e32 v231, v231
	v_mul_f32_e32 v104, v104, v224
	v_mul_f32_e32 v105, v105, v225
	v_mul_f32_e32 v106, v106, v226
	v_mul_f32_e32 v107, v107, v227
	v_mul_f32_e32 v96, v96, v228
	v_mul_f32_e32 v97, v97, v229
	v_mul_f32_e32 v98, v98, v230
	v_mul_f32_e32 v99, v99, v231
	v_cvt_pk_bf16_f32 v184, v104, v105
	v_cvt_pk_bf16_f32 v185, v106, v107
	v_cvt_pk_bf16_f32 v186, v96, v97
	v_cvt_pk_bf16_f32 v187, v98, v99
	global_store_dwordx4 v[220:221], v[184:187], off
	v_lshl_add_u64 v[220:221], v[220:221], 0, s[88:89]
	v_mul_f32_e32 v224, v92, v236
	v_mul_f32_e32 v225, v93, v236
	v_mul_f32_e32 v226, v94, v236
	v_mul_f32_e32 v227, v95, v236
	v_mul_f32_e32 v228, v84, v236
	v_mul_f32_e32 v229, v85, v236
	v_mul_f32_e32 v230, v86, v236
	v_mul_f32_e32 v231, v87, v236
	v_mul_f32_e32 v88, v92, v88
	v_mul_f32_e32 v89, v93, v89
	v_mul_f32_e32 v90, v94, v90
	v_mul_f32_e32 v91, v95, v91
	v_mul_f32_e32 v80, v84, v80
	v_mul_f32_e32 v81, v85, v81
	v_mul_f32_e32 v82, v86, v82
	v_mul_f32_e32 v83, v87, v83
	v_exp_f32_e32 v224, v224
	v_exp_f32_e32 v225, v225
	v_exp_f32_e32 v226, v226
	v_exp_f32_e32 v227, v227
	v_exp_f32_e32 v228, v228
	v_exp_f32_e32 v229, v229
	v_exp_f32_e32 v230, v230
	v_exp_f32_e32 v231, v231
	v_mul_f32_e32 v88, v88, v237
	v_mul_f32_e32 v89, v89, v237
	v_mul_f32_e32 v90, v90, v237
	v_mul_f32_e32 v91, v91, v237
	v_mul_f32_e32 v80, v80, v237
	v_mul_f32_e32 v81, v81, v237
	v_mul_f32_e32 v82, v82, v237
	v_mul_f32_e32 v83, v83, v237
	v_add_f32_e32 v224, 1.0, v224
	v_add_f32_e32 v225, 1.0, v225
	v_add_f32_e32 v226, 1.0, v226
	v_add_f32_e32 v227, 1.0, v227
	v_add_f32_e32 v228, 1.0, v228
	v_add_f32_e32 v229, 1.0, v229
	v_add_f32_e32 v230, 1.0, v230
	v_add_f32_e32 v231, 1.0, v231
	v_rcp_f32_e32 v224, v224
	v_rcp_f32_e32 v225, v225
	v_rcp_f32_e32 v226, v226
	v_rcp_f32_e32 v227, v227
	v_rcp_f32_e32 v228, v228
	v_rcp_f32_e32 v229, v229
	v_rcp_f32_e32 v230, v230
	v_rcp_f32_e32 v231, v231
	v_mul_f32_e32 v88, v88, v224
	v_mul_f32_e32 v89, v89, v225
	v_mul_f32_e32 v90, v90, v226
	v_mul_f32_e32 v91, v91, v227
	v_mul_f32_e32 v80, v80, v228
	v_mul_f32_e32 v81, v81, v229
	v_mul_f32_e32 v82, v82, v230
	v_mul_f32_e32 v83, v83, v231
	v_cvt_pk_bf16_f32 v188, v88, v89
	v_cvt_pk_bf16_f32 v189, v90, v91
	v_cvt_pk_bf16_f32 v190, v80, v81
	v_cvt_pk_bf16_f32 v191, v82, v83
	global_store_dwordx4 v[220:221], v[188:191], off
	v_lshl_add_u64 v[220:221], v[220:221], 0, s[88:89]
	v_mul_f32_e32 v224, v76, v238
	v_mul_f32_e32 v225, v77, v238
	v_mul_f32_e32 v226, v78, v238
	v_mul_f32_e32 v227, v79, v238
	v_mul_f32_e32 v228, v68, v238
	v_mul_f32_e32 v229, v69, v238
	v_mul_f32_e32 v230, v70, v238
	v_mul_f32_e32 v231, v71, v238
	v_mul_f32_e32 v72, v76, v72
	v_mul_f32_e32 v73, v77, v73
	v_mul_f32_e32 v74, v78, v74
	v_mul_f32_e32 v75, v79, v75
	v_mul_f32_e32 v64, v68, v64
	v_mul_f32_e32 v65, v69, v65
	v_mul_f32_e32 v66, v70, v66
	v_mul_f32_e32 v67, v71, v67
	v_exp_f32_e32 v224, v224
	v_exp_f32_e32 v225, v225
	v_exp_f32_e32 v226, v226
	v_exp_f32_e32 v227, v227
	v_exp_f32_e32 v228, v228
	v_exp_f32_e32 v229, v229
	v_exp_f32_e32 v230, v230
	v_exp_f32_e32 v231, v231
	v_mul_f32_e32 v72, v72, v239
	v_mul_f32_e32 v73, v73, v239
	v_mul_f32_e32 v74, v74, v239
	v_mul_f32_e32 v75, v75, v239
	v_mul_f32_e32 v64, v64, v239
	v_mul_f32_e32 v65, v65, v239
	v_mul_f32_e32 v66, v66, v239
	v_mul_f32_e32 v67, v67, v239
	v_add_f32_e32 v224, 1.0, v224
	v_add_f32_e32 v225, 1.0, v225
	v_add_f32_e32 v226, 1.0, v226
	v_add_f32_e32 v227, 1.0, v227
	v_add_f32_e32 v228, 1.0, v228
	v_add_f32_e32 v229, 1.0, v229
	v_add_f32_e32 v230, 1.0, v230
	v_add_f32_e32 v231, 1.0, v231
	v_rcp_f32_e32 v224, v224
	v_rcp_f32_e32 v225, v225
	v_rcp_f32_e32 v226, v226
	v_rcp_f32_e32 v227, v227
	v_rcp_f32_e32 v228, v228
	v_rcp_f32_e32 v229, v229
	v_rcp_f32_e32 v230, v230
	v_rcp_f32_e32 v231, v231
	v_mul_f32_e32 v72, v72, v224
	v_mul_f32_e32 v73, v73, v225
	v_mul_f32_e32 v74, v74, v226
	v_mul_f32_e32 v75, v75, v227
	v_mul_f32_e32 v64, v64, v228
	v_mul_f32_e32 v65, v65, v229
	v_mul_f32_e32 v66, v66, v230
	v_mul_f32_e32 v67, v67, v231
	v_cvt_pk_bf16_f32 v192, v72, v73
	v_cvt_pk_bf16_f32 v193, v74, v75
	v_cvt_pk_bf16_f32 v194, v64, v65
	v_cvt_pk_bf16_f32 v195, v66, v67
	global_store_dwordx4 v[220:221], v[192:195], off
	v_lshl_add_u64 v[220:221], v[220:221], 0, s[90:91]
	v_mul_f32_e32 v224, v60, v240
	v_mul_f32_e32 v225, v61, v240
	v_mul_f32_e32 v226, v62, v240
	v_mul_f32_e32 v227, v63, v240
	v_mul_f32_e32 v228, v52, v240
	v_mul_f32_e32 v229, v53, v240
	v_mul_f32_e32 v230, v54, v240
	v_mul_f32_e32 v231, v55, v240
	v_mul_f32_e32 v56, v60, v56
	v_mul_f32_e32 v57, v61, v57
	v_mul_f32_e32 v58, v62, v58
	v_mul_f32_e32 v59, v63, v59
	v_mul_f32_e32 v48, v52, v48
	v_mul_f32_e32 v49, v53, v49
	v_mul_f32_e32 v50, v54, v50
	v_mul_f32_e32 v51, v55, v51
	v_exp_f32_e32 v224, v224
	v_exp_f32_e32 v225, v225
	v_exp_f32_e32 v226, v226
	v_exp_f32_e32 v227, v227
	v_exp_f32_e32 v228, v228
	v_exp_f32_e32 v229, v229
	v_exp_f32_e32 v230, v230
	v_exp_f32_e32 v231, v231
	v_mul_f32_e32 v56, v56, v241
	v_mul_f32_e32 v57, v57, v241
	v_mul_f32_e32 v58, v58, v241
	v_mul_f32_e32 v59, v59, v241
	v_mul_f32_e32 v48, v48, v241
	v_mul_f32_e32 v49, v49, v241
	v_mul_f32_e32 v50, v50, v241
	v_mul_f32_e32 v51, v51, v241
	v_add_f32_e32 v224, 1.0, v224
	v_add_f32_e32 v225, 1.0, v225
	v_add_f32_e32 v226, 1.0, v226
	v_add_f32_e32 v227, 1.0, v227
	v_add_f32_e32 v228, 1.0, v228
	v_add_f32_e32 v229, 1.0, v229
	v_add_f32_e32 v230, 1.0, v230
	v_add_f32_e32 v231, 1.0, v231
	v_rcp_f32_e32 v224, v224
	v_rcp_f32_e32 v225, v225
	v_rcp_f32_e32 v226, v226
	v_rcp_f32_e32 v227, v227
	v_rcp_f32_e32 v228, v228
	v_rcp_f32_e32 v229, v229
	v_rcp_f32_e32 v230, v230
	v_rcp_f32_e32 v231, v231
	v_mul_f32_e32 v56, v56, v224
	v_mul_f32_e32 v57, v57, v225
	v_mul_f32_e32 v58, v58, v226
	v_mul_f32_e32 v59, v59, v227
	v_mul_f32_e32 v48, v48, v228
	v_mul_f32_e32 v49, v49, v229
	v_mul_f32_e32 v50, v50, v230
	v_mul_f32_e32 v51, v51, v231
	v_cvt_pk_bf16_f32 v196, v56, v57
	v_cvt_pk_bf16_f32 v197, v58, v59
	v_cvt_pk_bf16_f32 v198, v48, v49
	v_cvt_pk_bf16_f32 v199, v50, v51
	global_store_dwordx4 v[220:221], v[196:199], off
	v_lshl_add_u64 v[220:221], v[220:221], 0, s[88:89]
	v_mul_f32_e32 v224, v44, v242
	v_mul_f32_e32 v225, v45, v242
	v_mul_f32_e32 v226, v46, v242
	v_mul_f32_e32 v227, v47, v242
	v_mul_f32_e32 v228, v36, v242
	v_mul_f32_e32 v229, v37, v242
	v_mul_f32_e32 v230, v38, v242
	v_mul_f32_e32 v231, v39, v242
	v_mul_f32_e32 v40, v44, v40
	v_mul_f32_e32 v41, v45, v41
	v_mul_f32_e32 v42, v46, v42
	v_mul_f32_e32 v43, v47, v43
	v_mul_f32_e32 v32, v36, v32
	v_mul_f32_e32 v33, v37, v33
	v_mul_f32_e32 v34, v38, v34
	v_mul_f32_e32 v35, v39, v35
	v_exp_f32_e32 v224, v224
	v_exp_f32_e32 v225, v225
	v_exp_f32_e32 v226, v226
	v_exp_f32_e32 v227, v227
	v_exp_f32_e32 v228, v228
	v_exp_f32_e32 v229, v229
	v_exp_f32_e32 v230, v230
	v_exp_f32_e32 v231, v231
	v_mul_f32_e32 v40, v40, v243
	v_mul_f32_e32 v41, v41, v243
	v_mul_f32_e32 v42, v42, v243
	v_mul_f32_e32 v43, v43, v243
	v_mul_f32_e32 v32, v32, v243
	v_mul_f32_e32 v33, v33, v243
	v_mul_f32_e32 v34, v34, v243
	v_mul_f32_e32 v35, v35, v243
	v_add_f32_e32 v224, 1.0, v224
	v_add_f32_e32 v225, 1.0, v225
	v_add_f32_e32 v226, 1.0, v226
	v_add_f32_e32 v227, 1.0, v227
	v_add_f32_e32 v228, 1.0, v228
	v_add_f32_e32 v229, 1.0, v229
	v_add_f32_e32 v230, 1.0, v230
	v_add_f32_e32 v231, 1.0, v231
	v_rcp_f32_e32 v224, v224
	v_rcp_f32_e32 v225, v225
	v_rcp_f32_e32 v226, v226
	v_rcp_f32_e32 v227, v227
	v_rcp_f32_e32 v228, v228
	v_rcp_f32_e32 v229, v229
	v_rcp_f32_e32 v230, v230
	v_rcp_f32_e32 v231, v231
	v_mul_f32_e32 v40, v40, v224
	v_mul_f32_e32 v41, v41, v225
	v_mul_f32_e32 v42, v42, v226
	v_mul_f32_e32 v43, v43, v227
	v_mul_f32_e32 v32, v32, v228
	v_mul_f32_e32 v33, v33, v229
	v_mul_f32_e32 v34, v34, v230
	v_mul_f32_e32 v35, v35, v231
	v_cvt_pk_bf16_f32 v200, v40, v41
	v_cvt_pk_bf16_f32 v201, v42, v43
	v_cvt_pk_bf16_f32 v202, v32, v33
	v_cvt_pk_bf16_f32 v203, v34, v35
	global_store_dwordx4 v[220:221], v[200:203], off
	v_lshl_add_u64 v[220:221], v[220:221], 0, s[88:89]
	v_mul_f32_e32 v224, v28, v244
	v_mul_f32_e32 v225, v29, v244
	v_mul_f32_e32 v226, v30, v244
	v_mul_f32_e32 v227, v31, v244
	v_mul_f32_e32 v228, v20, v244
	v_mul_f32_e32 v229, v21, v244
	v_mul_f32_e32 v230, v22, v244
	v_mul_f32_e32 v231, v23, v244
	v_mul_f32_e32 v24, v28, v24
	v_mul_f32_e32 v25, v29, v25
	v_mul_f32_e32 v26, v30, v26
	v_mul_f32_e32 v27, v31, v27
	v_mul_f32_e32 v16, v20, v16
	v_mul_f32_e32 v17, v21, v17
	v_mul_f32_e32 v18, v22, v18
	v_mul_f32_e32 v19, v23, v19
	v_exp_f32_e32 v224, v224
	v_exp_f32_e32 v225, v225
	v_exp_f32_e32 v226, v226
	v_exp_f32_e32 v227, v227
	v_exp_f32_e32 v228, v228
	v_exp_f32_e32 v229, v229
	v_exp_f32_e32 v230, v230
	v_exp_f32_e32 v231, v231
	v_mul_f32_e32 v24, v24, v245
	v_mul_f32_e32 v25, v25, v245
	v_mul_f32_e32 v26, v26, v245
	v_mul_f32_e32 v27, v27, v245
	v_mul_f32_e32 v16, v16, v245
	v_mul_f32_e32 v17, v17, v245
	v_mul_f32_e32 v18, v18, v245
	v_mul_f32_e32 v19, v19, v245
	v_add_f32_e32 v224, 1.0, v224
	v_add_f32_e32 v225, 1.0, v225
	v_add_f32_e32 v226, 1.0, v226
	v_add_f32_e32 v227, 1.0, v227
	v_add_f32_e32 v228, 1.0, v228
	v_add_f32_e32 v229, 1.0, v229
	v_add_f32_e32 v230, 1.0, v230
	v_add_f32_e32 v231, 1.0, v231
	v_rcp_f32_e32 v224, v224
	v_rcp_f32_e32 v225, v225
	v_rcp_f32_e32 v226, v226
	v_rcp_f32_e32 v227, v227
	v_rcp_f32_e32 v228, v228
	v_rcp_f32_e32 v229, v229
	v_rcp_f32_e32 v230, v230
	v_rcp_f32_e32 v231, v231
	v_mul_f32_e32 v24, v24, v224
	v_mul_f32_e32 v25, v25, v225
	v_mul_f32_e32 v26, v26, v226
	v_mul_f32_e32 v27, v27, v227
	v_mul_f32_e32 v16, v16, v228
	v_mul_f32_e32 v17, v17, v229
	v_mul_f32_e32 v18, v18, v230
	v_mul_f32_e32 v19, v19, v231
	v_cvt_pk_bf16_f32 v204, v24, v25
	v_cvt_pk_bf16_f32 v205, v26, v27
	v_cvt_pk_bf16_f32 v206, v16, v17
	v_cvt_pk_bf16_f32 v207, v18, v19
	global_store_dwordx4 v[220:221], v[204:207], off
	v_lshl_add_u64 v[220:221], v[220:221], 0, s[88:89]
	v_mul_f32_e32 v224, v12, v246
	v_mul_f32_e32 v225, v13, v246
	v_mul_f32_e32 v226, v14, v246
	v_mul_f32_e32 v227, v15, v246
	v_mul_f32_e32 v228, v4, v246
	v_mul_f32_e32 v229, v5, v246
	v_mul_f32_e32 v230, v6, v246
	v_mul_f32_e32 v231, v7, v246
	v_mul_f32_e32 v8, v12, v8
	v_mul_f32_e32 v9, v13, v9
	v_mul_f32_e32 v10, v14, v10
	v_mul_f32_e32 v11, v15, v11
	v_mul_f32_e32 v0, v4, v0
	v_mul_f32_e32 v1, v5, v1
	v_mul_f32_e32 v2, v6, v2
	v_mul_f32_e32 v3, v7, v3
	v_exp_f32_e32 v224, v224
	v_exp_f32_e32 v225, v225
	v_exp_f32_e32 v226, v226
	v_exp_f32_e32 v227, v227
	v_exp_f32_e32 v228, v228
	v_exp_f32_e32 v229, v229
	v_exp_f32_e32 v230, v230
	v_exp_f32_e32 v231, v231
	v_mul_f32_e32 v8, v8, v247
	v_mul_f32_e32 v9, v9, v247
	v_mul_f32_e32 v10, v10, v247
	v_mul_f32_e32 v11, v11, v247
	v_mul_f32_e32 v0, v0, v247
	v_mul_f32_e32 v1, v1, v247
	v_mul_f32_e32 v2, v2, v247
	v_mul_f32_e32 v3, v3, v247
	v_add_f32_e32 v224, 1.0, v224
	v_add_f32_e32 v225, 1.0, v225
	v_add_f32_e32 v226, 1.0, v226
	v_add_f32_e32 v227, 1.0, v227
	v_add_f32_e32 v228, 1.0, v228
	v_add_f32_e32 v229, 1.0, v229
	v_add_f32_e32 v230, 1.0, v230
	v_add_f32_e32 v231, 1.0, v231
	v_rcp_f32_e32 v224, v224
	v_rcp_f32_e32 v225, v225
	v_rcp_f32_e32 v226, v226
	v_rcp_f32_e32 v227, v227
	v_rcp_f32_e32 v228, v228
	v_rcp_f32_e32 v229, v229
	v_rcp_f32_e32 v230, v230
	v_rcp_f32_e32 v231, v231
	v_mul_f32_e32 v8, v8, v224
	v_mul_f32_e32 v9, v9, v225
	v_mul_f32_e32 v10, v10, v226
	v_mul_f32_e32 v11, v11, v227
	v_mul_f32_e32 v0, v0, v228
	v_mul_f32_e32 v1, v1, v229
	v_mul_f32_e32 v2, v2, v230
	v_mul_f32_e32 v3, v3, v231
	v_cvt_pk_bf16_f32 v208, v8, v9
	v_cvt_pk_bf16_f32 v209, v10, v11
	v_cvt_pk_bf16_f32 v210, v0, v1
	v_cvt_pk_bf16_f32 v211, v2, v3
	global_store_dwordx4 v[220:221], v[208:211], off
	s_andn2_b64 vcc, exec, s[4:5]
	s_mov_b64 s[4:5], -1
	s_cbranch_vccnz .LBB0_66
	s_andn2_b64 vcc, exec, s[10:11]
	s_cbranch_vccnz .LBB0_65
	s_barrier
	s_branch .LBB0_65

.LBB0_625:
	s_movk_i32 s84, 0x1600
	s_mov_b64 s[88:89], 0x16000
	s_mov_b64 s[90:91], 0x6e000
	v_lshl_add_u32 v178, s55, 12, v168
	ds_read_b128 v[180:183], v178 offset:0
	ds_read_b128 v[184:187], v178 offset:256
	ds_read_b128 v[188:191], v178 offset:512
	ds_read_b128 v[192:195], v178 offset:768
	ds_read_b128 v[196:199], v178 offset:2048
	ds_read_b128 v[200:203], v178 offset:2304
	ds_read_b128 v[204:207], v178 offset:2560
	ds_read_b128 v[208:211], v178 offset:2816
	v_lshl_add_u32 v218, s34, 8, v166
	v_lshl_or_b32 v222, s36, 7, v169
	v_mov_b32_e32 v223, 0
	v_lshlrev_b32_e32 v222, 1, v222
	v_mad_u64_u32 v[220:221], s[82:83], v218, s84, v[142:143]
	v_lshl_add_u64 v[220:221], v[222:223], 0, v[220:221]
	s_waitcnt lgkmcnt(0)
	v_add_f32_e32 v180, v180, v181
	v_add_f32_e32 v184, v184, v185
	v_add_f32_e32 v188, v188, v189
	v_add_f32_e32 v192, v192, v193
	v_add_f32_e32 v196, v196, v197
	v_add_f32_e32 v200, v200, v201
	v_add_f32_e32 v204, v204, v205
	v_add_f32_e32 v208, v208, v209
	v_add_f32_e32 v182, v182, v183
	v_add_f32_e32 v186, v186, v187
	v_add_f32_e32 v190, v190, v191
	v_add_f32_e32 v194, v194, v195
	v_add_f32_e32 v198, v198, v199
	v_add_f32_e32 v202, v202, v203
	v_add_f32_e32 v206, v206, v207
	v_add_f32_e32 v210, v210, v211
	v_add_f32_e32 v180, v180, v182
	v_add_f32_e32 v184, v184, v186
	v_add_f32_e32 v188, v188, v190
	v_add_f32_e32 v192, v192, v194
	v_add_f32_e32 v196, v196, v198
	v_add_f32_e32 v200, v200, v202
	v_add_f32_e32 v204, v204, v206
	v_add_f32_e32 v208, v208, v210
	v_fmamk_f32 v180, v180, 0x3a800000, v171
	v_fmamk_f32 v184, v184, 0x3a800000, v171
	v_fmamk_f32 v188, v188, 0x3a800000, v171
	v_fmamk_f32 v192, v192, 0x3a800000, v171
	v_fmamk_f32 v196, v196, 0x3a800000, v171
	v_fmamk_f32 v200, v200, 0x3a800000, v171
	v_fmamk_f32 v204, v204, 0x3a800000, v171
	v_fmamk_f32 v208, v208, 0x3a800000, v171
	v_rsq_f32_e32 v180, v180
	v_rsq_f32_e32 v184, v184
	v_rsq_f32_e32 v188, v188
	v_rsq_f32_e32 v192, v192
	v_rsq_f32_e32 v196, v196
	v_rsq_f32_e32 v200, v200
	v_rsq_f32_e32 v204, v204
	v_rsq_f32_e32 v208, v208
	v_mul_f32_e32 v232, 0xbfb8aa3b, v180
	v_mul_f32_e32 v234, 0xbfb8aa3b, v184
	v_mul_f32_e32 v236, 0xbfb8aa3b, v188
	v_mul_f32_e32 v238, 0xbfb8aa3b, v192
	v_mul_f32_e32 v240, 0xbfb8aa3b, v196
	v_mul_f32_e32 v242, 0xbfb8aa3b, v200
	v_mul_f32_e32 v244, 0xbfb8aa3b, v204
	v_mul_f32_e32 v246, 0xbfb8aa3b, v208
	v_mul_f32_e32 v233, v180, v180
	v_mul_f32_e32 v235, v184, v184
	v_mul_f32_e32 v237, v188, v188
	v_mul_f32_e32 v239, v192, v192
	v_mul_f32_e32 v241, v196, v196
	v_mul_f32_e32 v243, v200, v200
	v_mul_f32_e32 v245, v204, v204
	v_mul_f32_e32 v247, v208, v208
	v_mul_f32_e32 v224, v124, v232
	v_mul_f32_e32 v225, v125, v232
	v_mul_f32_e32 v226, v126, v232
	v_mul_f32_e32 v227, v127, v232
	v_mul_f32_e32 v228, v116, v232
	v_mul_f32_e32 v229, v117, v232
	v_mul_f32_e32 v230, v118, v232
	v_mul_f32_e32 v231, v119, v232
	v_mul_f32_e32 v120, v124, v120
	v_mul_f32_e32 v121, v125, v121
	v_mul_f32_e32 v122, v126, v122
	v_mul_f32_e32 v123, v127, v123
	v_mul_f32_e32 v112, v116, v112
	v_mul_f32_e32 v113, v117, v113
	v_mul_f32_e32 v114, v118, v114
	v_mul_f32_e32 v115, v119, v115
	v_exp_f32_e32 v224, v224
	v_exp_f32_e32 v225, v225
	v_exp_f32_e32 v226, v226
	v_exp_f32_e32 v227, v227
	v_exp_f32_e32 v228, v228
	v_exp_f32_e32 v229, v229
	v_exp_f32_e32 v230, v230
	v_exp_f32_e32 v231, v231
	v_mul_f32_e32 v120, v120, v233
	v_mul_f32_e32 v121, v121, v233
	v_mul_f32_e32 v122, v122, v233
	v_mul_f32_e32 v123, v123, v233
	v_mul_f32_e32 v112, v112, v233
	v_mul_f32_e32 v113, v113, v233
	v_mul_f32_e32 v114, v114, v233
	v_mul_f32_e32 v115, v115, v233
	v_add_f32_e32 v224, 1.0, v224
	v_add_f32_e32 v225, 1.0, v225
	v_add_f32_e32 v226, 1.0, v226
	v_add_f32_e32 v227, 1.0, v227
	v_add_f32_e32 v228, 1.0, v228
	v_add_f32_e32 v229, 1.0, v229
	v_add_f32_e32 v230, 1.0, v230
	v_add_f32_e32 v231, 1.0, v231
	v_rcp_f32_e32 v224, v224
	v_rcp_f32_e32 v225, v225
	v_rcp_f32_e32 v226, v226
	v_rcp_f32_e32 v227, v227
	v_rcp_f32_e32 v228, v228
	v_rcp_f32_e32 v229, v229
	v_rcp_f32_e32 v230, v230
	v_rcp_f32_e32 v231, v231
	v_mul_f32_e32 v120, v120, v224
	v_mul_f32_e32 v121, v121, v225
	v_mul_f32_e32 v122, v122, v226
	v_mul_f32_e32 v123, v123, v227
	v_mul_f32_e32 v112, v112, v228
	v_mul_f32_e32 v113, v113, v229
	v_mul_f32_e32 v114, v114, v230
	v_mul_f32_e32 v115, v115, v231
	v_cvt_pk_bf16_f32 v180, v120, v121
	v_cvt_pk_bf16_f32 v181, v122, v123
	v_cvt_pk_bf16_f32 v182, v112, v113
	v_cvt_pk_bf16_f32 v183, v114, v115
	global_store_dwordx4 v[220:221], v[180:183], off
	v_lshl_add_u64 v[220:221], v[220:221], 0, s[88:89]
	v_mul_f32_e32 v224, v108, v234
	v_mul_f32_e32 v225, v109, v234
	v_mul_f32_e32 v226, v110, v234
	v_mul_f32_e32 v227, v111, v234
	v_mul_f32_e32 v228, v100, v234
	v_mul_f32_e32 v229, v101, v234
	v_mul_f32_e32 v230, v102, v234
	v_mul_f32_e32 v231, v103, v234
	v_mul_f32_e32 v104, v108, v104
	v_mul_f32_e32 v105, v109, v105
	v_mul_f32_e32 v106, v110, v106
	v_mul_f32_e32 v107, v111, v107
	v_mul_f32_e32 v96, v100, v96
	v_mul_f32_e32 v97, v101, v97
	v_mul_f32_e32 v98, v102, v98
	v_mul_f32_e32 v99, v103, v99
	v_exp_f32_e32 v224, v224
	v_exp_f32_e32 v225, v225
	v_exp_f32_e32 v226, v226
	v_exp_f32_e32 v227, v227
	v_exp_f32_e32 v228, v228
	v_exp_f32_e32 v229, v229
	v_exp_f32_e32 v230, v230
	v_exp_f32_e32 v231, v231
	v_mul_f32_e32 v104, v104, v235
	v_mul_f32_e32 v105, v105, v235
	v_mul_f32_e32 v106, v106, v235
	v_mul_f32_e32 v107, v107, v235
	v_mul_f32_e32 v96, v96, v235
	v_mul_f32_e32 v97, v97, v235
	v_mul_f32_e32 v98, v98, v235
	v_mul_f32_e32 v99, v99, v235
	v_add_f32_e32 v224, 1.0, v224
	v_add_f32_e32 v225, 1.0, v225
	v_add_f32_e32 v226, 1.0, v226
	v_add_f32_e32 v227, 1.0, v227
	v_add_f32_e32 v228, 1.0, v228
	v_add_f32_e32 v229, 1.0, v229
	v_add_f32_e32 v230, 1.0, v230
	v_add_f32_e32 v231, 1.0, v231
	v_rcp_f32_e32 v224, v224
	v_rcp_f32_e32 v225, v225
	v_rcp_f32_e32 v226, v226
	v_rcp_f32_e32 v227, v227
	v_rcp_f32_e32 v228, v228
	v_rcp_f32_e32 v229, v229
	v_rcp_f32_e32 v230, v230
	v_rcp_f32_e32 v231, v231
	v_mul_f32_e32 v104, v104, v224
	v_mul_f32_e32 v105, v105, v225
	v_mul_f32_e32 v106, v106, v226
	v_mul_f32_e32 v107, v107, v227
	v_mul_f32_e32 v96, v96, v228
	v_mul_f32_e32 v97, v97, v229
	v_mul_f32_e32 v98, v98, v230
	v_mul_f32_e32 v99, v99, v231
	v_cvt_pk_bf16_f32 v184, v104, v105
	v_cvt_pk_bf16_f32 v185, v106, v107
	v_cvt_pk_bf16_f32 v186, v96, v97
	v_cvt_pk_bf16_f32 v187, v98, v99
	global_store_dwordx4 v[220:221], v[184:187], off
	v_lshl_add_u64 v[220:221], v[220:221], 0, s[88:89]
	v_mul_f32_e32 v224, v92, v236
	v_mul_f32_e32 v225, v93, v236
	v_mul_f32_e32 v226, v94, v236
	v_mul_f32_e32 v227, v95, v236
	v_mul_f32_e32 v228, v84, v236
	v_mul_f32_e32 v229, v85, v236
	v_mul_f32_e32 v230, v86, v236
	v_mul_f32_e32 v231, v87, v236
	v_mul_f32_e32 v88, v92, v88
	v_mul_f32_e32 v89, v93, v89
	v_mul_f32_e32 v90, v94, v90
	v_mul_f32_e32 v91, v95, v91
	v_mul_f32_e32 v80, v84, v80
	v_mul_f32_e32 v81, v85, v81
	v_mul_f32_e32 v82, v86, v82
	v_mul_f32_e32 v83, v87, v83
	v_exp_f32_e32 v224, v224
	v_exp_f32_e32 v225, v225
	v_exp_f32_e32 v226, v226
	v_exp_f32_e32 v227, v227
	v_exp_f32_e32 v228, v228
	v_exp_f32_e32 v229, v229
	v_exp_f32_e32 v230, v230
	v_exp_f32_e32 v231, v231
	v_mul_f32_e32 v88, v88, v237
	v_mul_f32_e32 v89, v89, v237
	v_mul_f32_e32 v90, v90, v237
	v_mul_f32_e32 v91, v91, v237
	v_mul_f32_e32 v80, v80, v237
	v_mul_f32_e32 v81, v81, v237
	v_mul_f32_e32 v82, v82, v237
	v_mul_f32_e32 v83, v83, v237
	v_add_f32_e32 v224, 1.0, v224
	v_add_f32_e32 v225, 1.0, v225
	v_add_f32_e32 v226, 1.0, v226
	v_add_f32_e32 v227, 1.0, v227
	v_add_f32_e32 v228, 1.0, v228
	v_add_f32_e32 v229, 1.0, v229
	v_add_f32_e32 v230, 1.0, v230
	v_add_f32_e32 v231, 1.0, v231
	v_rcp_f32_e32 v224, v224
	v_rcp_f32_e32 v225, v225
	v_rcp_f32_e32 v226, v226
	v_rcp_f32_e32 v227, v227
	v_rcp_f32_e32 v228, v228
	v_rcp_f32_e32 v229, v229
	v_rcp_f32_e32 v230, v230
	v_rcp_f32_e32 v231, v231
	v_mul_f32_e32 v88, v88, v224
	v_mul_f32_e32 v89, v89, v225
	v_mul_f32_e32 v90, v90, v226
	v_mul_f32_e32 v91, v91, v227
	v_mul_f32_e32 v80, v80, v228
	v_mul_f32_e32 v81, v81, v229
	v_mul_f32_e32 v82, v82, v230
	v_mul_f32_e32 v83, v83, v231
	v_cvt_pk_bf16_f32 v188, v88, v89
	v_cvt_pk_bf16_f32 v189, v90, v91
	v_cvt_pk_bf16_f32 v190, v80, v81
	v_cvt_pk_bf16_f32 v191, v82, v83
	global_store_dwordx4 v[220:221], v[188:191], off
	v_lshl_add_u64 v[220:221], v[220:221], 0, s[88:89]
	v_mul_f32_e32 v224, v76, v238
	v_mul_f32_e32 v225, v77, v238
	v_mul_f32_e32 v226, v78, v238
	v_mul_f32_e32 v227, v79, v238
	v_mul_f32_e32 v228, v68, v238
	v_mul_f32_e32 v229, v69, v238
	v_mul_f32_e32 v230, v70, v238
	v_mul_f32_e32 v231, v71, v238
	v_mul_f32_e32 v72, v76, v72
	v_mul_f32_e32 v73, v77, v73
	v_mul_f32_e32 v74, v78, v74
	v_mul_f32_e32 v75, v79, v75
	v_mul_f32_e32 v64, v68, v64
	v_mul_f32_e32 v65, v69, v65
	v_mul_f32_e32 v66, v70, v66
	v_mul_f32_e32 v67, v71, v67
	v_exp_f32_e32 v224, v224
	v_exp_f32_e32 v225, v225
	v_exp_f32_e32 v226, v226
	v_exp_f32_e32 v227, v227
	v_exp_f32_e32 v228, v228
	v_exp_f32_e32 v229, v229
	v_exp_f32_e32 v230, v230
	v_exp_f32_e32 v231, v231
	v_mul_f32_e32 v72, v72, v239
	v_mul_f32_e32 v73, v73, v239
	v_mul_f32_e32 v74, v74, v239
	v_mul_f32_e32 v75, v75, v239
	v_mul_f32_e32 v64, v64, v239
	v_mul_f32_e32 v65, v65, v239
	v_mul_f32_e32 v66, v66, v239
	v_mul_f32_e32 v67, v67, v239
	v_add_f32_e32 v224, 1.0, v224
	v_add_f32_e32 v225, 1.0, v225
	v_add_f32_e32 v226, 1.0, v226
	v_add_f32_e32 v227, 1.0, v227
	v_add_f32_e32 v228, 1.0, v228
	v_add_f32_e32 v229, 1.0, v229
	v_add_f32_e32 v230, 1.0, v230
	v_add_f32_e32 v231, 1.0, v231
	v_rcp_f32_e32 v224, v224
	v_rcp_f32_e32 v225, v225
	v_rcp_f32_e32 v226, v226
	v_rcp_f32_e32 v227, v227
	v_rcp_f32_e32 v228, v228
	v_rcp_f32_e32 v229, v229
	v_rcp_f32_e32 v230, v230
	v_rcp_f32_e32 v231, v231
	v_mul_f32_e32 v72, v72, v224
	v_mul_f32_e32 v73, v73, v225
	v_mul_f32_e32 v74, v74, v226
	v_mul_f32_e32 v75, v75, v227
	v_mul_f32_e32 v64, v64, v228
	v_mul_f32_e32 v65, v65, v229
	v_mul_f32_e32 v66, v66, v230
	v_mul_f32_e32 v67, v67, v231
	v_cvt_pk_bf16_f32 v192, v72, v73
	v_cvt_pk_bf16_f32 v193, v74, v75
	v_cvt_pk_bf16_f32 v194, v64, v65
	v_cvt_pk_bf16_f32 v195, v66, v67
	global_store_dwordx4 v[220:221], v[192:195], off
	v_lshl_add_u64 v[220:221], v[220:221], 0, s[90:91]
	v_mul_f32_e32 v224, v60, v240
	v_mul_f32_e32 v225, v61, v240
	v_mul_f32_e32 v226, v62, v240
	v_mul_f32_e32 v227, v63, v240
	v_mul_f32_e32 v228, v52, v240
	v_mul_f32_e32 v229, v53, v240
	v_mul_f32_e32 v230, v54, v240
	v_mul_f32_e32 v231, v55, v240
	v_mul_f32_e32 v56, v60, v56
	v_mul_f32_e32 v57, v61, v57
	v_mul_f32_e32 v58, v62, v58
	v_mul_f32_e32 v59, v63, v59
	v_mul_f32_e32 v48, v52, v48
	v_mul_f32_e32 v49, v53, v49
	v_mul_f32_e32 v50, v54, v50
	v_mul_f32_e32 v51, v55, v51
	v_exp_f32_e32 v224, v224
	v_exp_f32_e32 v225, v225
	v_exp_f32_e32 v226, v226
	v_exp_f32_e32 v227, v227
	v_exp_f32_e32 v228, v228
	v_exp_f32_e32 v229, v229
	v_exp_f32_e32 v230, v230
	v_exp_f32_e32 v231, v231
	v_mul_f32_e32 v56, v56, v241
	v_mul_f32_e32 v57, v57, v241
	v_mul_f32_e32 v58, v58, v241
	v_mul_f32_e32 v59, v59, v241
	v_mul_f32_e32 v48, v48, v241
	v_mul_f32_e32 v49, v49, v241
	v_mul_f32_e32 v50, v50, v241
	v_mul_f32_e32 v51, v51, v241
	v_add_f32_e32 v224, 1.0, v224
	v_add_f32_e32 v225, 1.0, v225
	v_add_f32_e32 v226, 1.0, v226
	v_add_f32_e32 v227, 1.0, v227
	v_add_f32_e32 v228, 1.0, v228
	v_add_f32_e32 v229, 1.0, v229
	v_add_f32_e32 v230, 1.0, v230
	v_add_f32_e32 v231, 1.0, v231
	v_rcp_f32_e32 v224, v224
	v_rcp_f32_e32 v225, v225
	v_rcp_f32_e32 v226, v226
	v_rcp_f32_e32 v227, v227
	v_rcp_f32_e32 v228, v228
	v_rcp_f32_e32 v229, v229
	v_rcp_f32_e32 v230, v230
	v_rcp_f32_e32 v231, v231
	v_mul_f32_e32 v56, v56, v224
	v_mul_f32_e32 v57, v57, v225
	v_mul_f32_e32 v58, v58, v226
	v_mul_f32_e32 v59, v59, v227
	v_mul_f32_e32 v48, v48, v228
	v_mul_f32_e32 v49, v49, v229
	v_mul_f32_e32 v50, v50, v230
	v_mul_f32_e32 v51, v51, v231
	v_cvt_pk_bf16_f32 v196, v56, v57
	v_cvt_pk_bf16_f32 v197, v58, v59
	v_cvt_pk_bf16_f32 v198, v48, v49
	v_cvt_pk_bf16_f32 v199, v50, v51
	global_store_dwordx4 v[220:221], v[196:199], off
	v_lshl_add_u64 v[220:221], v[220:221], 0, s[88:89]
	v_mul_f32_e32 v224, v44, v242
	v_mul_f32_e32 v225, v45, v242
	v_mul_f32_e32 v226, v46, v242
	v_mul_f32_e32 v227, v47, v242
	v_mul_f32_e32 v228, v36, v242
	v_mul_f32_e32 v229, v37, v242
	v_mul_f32_e32 v230, v38, v242
	v_mul_f32_e32 v231, v39, v242
	v_mul_f32_e32 v40, v44, v40
	v_mul_f32_e32 v41, v45, v41
	v_mul_f32_e32 v42, v46, v42
	v_mul_f32_e32 v43, v47, v43
	v_mul_f32_e32 v32, v36, v32
	v_mul_f32_e32 v33, v37, v33
	v_mul_f32_e32 v34, v38, v34
	v_mul_f32_e32 v35, v39, v35
	v_exp_f32_e32 v224, v224
	v_exp_f32_e32 v225, v225
	v_exp_f32_e32 v226, v226
	v_exp_f32_e32 v227, v227
	v_exp_f32_e32 v228, v228
	v_exp_f32_e32 v229, v229
	v_exp_f32_e32 v230, v230
	v_exp_f32_e32 v231, v231
	v_mul_f32_e32 v40, v40, v243
	v_mul_f32_e32 v41, v41, v243
	v_mul_f32_e32 v42, v42, v243
	v_mul_f32_e32 v43, v43, v243
	v_mul_f32_e32 v32, v32, v243
	v_mul_f32_e32 v33, v33, v243
	v_mul_f32_e32 v34, v34, v243
	v_mul_f32_e32 v35, v35, v243
	v_add_f32_e32 v224, 1.0, v224
	v_add_f32_e32 v225, 1.0, v225
	v_add_f32_e32 v226, 1.0, v226
	v_add_f32_e32 v227, 1.0, v227
	v_add_f32_e32 v228, 1.0, v228
	v_add_f32_e32 v229, 1.0, v229
	v_add_f32_e32 v230, 1.0, v230
	v_add_f32_e32 v231, 1.0, v231
	v_rcp_f32_e32 v224, v224
	v_rcp_f32_e32 v225, v225
	v_rcp_f32_e32 v226, v226
	v_rcp_f32_e32 v227, v227
	v_rcp_f32_e32 v228, v228
	v_rcp_f32_e32 v229, v229
	v_rcp_f32_e32 v230, v230
	v_rcp_f32_e32 v231, v231
	v_mul_f32_e32 v40, v40, v224
	v_mul_f32_e32 v41, v41, v225
	v_mul_f32_e32 v42, v42, v226
	v_mul_f32_e32 v43, v43, v227
	v_mul_f32_e32 v32, v32, v228
	v_mul_f32_e32 v33, v33, v229
	v_mul_f32_e32 v34, v34, v230
	v_mul_f32_e32 v35, v35, v231
	v_cvt_pk_bf16_f32 v200, v40, v41
	v_cvt_pk_bf16_f32 v201, v42, v43
	v_cvt_pk_bf16_f32 v202, v32, v33
	v_cvt_pk_bf16_f32 v203, v34, v35
	global_store_dwordx4 v[220:221], v[200:203], off
	v_lshl_add_u64 v[220:221], v[220:221], 0, s[88:89]
	v_mul_f32_e32 v224, v28, v244
	v_mul_f32_e32 v225, v29, v244
	v_mul_f32_e32 v226, v30, v244
	v_mul_f32_e32 v227, v31, v244
	v_mul_f32_e32 v228, v20, v244
	v_mul_f32_e32 v229, v21, v244
	v_mul_f32_e32 v230, v22, v244
	v_mul_f32_e32 v231, v23, v244
	v_mul_f32_e32 v24, v28, v24
	v_mul_f32_e32 v25, v29, v25
	v_mul_f32_e32 v26, v30, v26
	v_mul_f32_e32 v27, v31, v27
	v_mul_f32_e32 v16, v20, v16
	v_mul_f32_e32 v17, v21, v17
	v_mul_f32_e32 v18, v22, v18
	v_mul_f32_e32 v19, v23, v19
	v_exp_f32_e32 v224, v224
	v_exp_f32_e32 v225, v225
	v_exp_f32_e32 v226, v226
	v_exp_f32_e32 v227, v227
	v_exp_f32_e32 v228, v228
	v_exp_f32_e32 v229, v229
	v_exp_f32_e32 v230, v230
	v_exp_f32_e32 v231, v231
	v_mul_f32_e32 v24, v24, v245
	v_mul_f32_e32 v25, v25, v245
	v_mul_f32_e32 v26, v26, v245
	v_mul_f32_e32 v27, v27, v245
	v_mul_f32_e32 v16, v16, v245
	v_mul_f32_e32 v17, v17, v245
	v_mul_f32_e32 v18, v18, v245
	v_mul_f32_e32 v19, v19, v245
	v_add_f32_e32 v224, 1.0, v224
	v_add_f32_e32 v225, 1.0, v225
	v_add_f32_e32 v226, 1.0, v226
	v_add_f32_e32 v227, 1.0, v227
	v_add_f32_e32 v228, 1.0, v228
	v_add_f32_e32 v229, 1.0, v229
	v_add_f32_e32 v230, 1.0, v230
	v_add_f32_e32 v231, 1.0, v231
	v_rcp_f32_e32 v224, v224
	v_rcp_f32_e32 v225, v225
	v_rcp_f32_e32 v226, v226
	v_rcp_f32_e32 v227, v227
	v_rcp_f32_e32 v228, v228
	v_rcp_f32_e32 v229, v229
	v_rcp_f32_e32 v230, v230
	v_rcp_f32_e32 v231, v231
	v_mul_f32_e32 v24, v24, v224
	v_mul_f32_e32 v25, v25, v225
	v_mul_f32_e32 v26, v26, v226
	v_mul_f32_e32 v27, v27, v227
	v_mul_f32_e32 v16, v16, v228
	v_mul_f32_e32 v17, v17, v229
	v_mul_f32_e32 v18, v18, v230
	v_mul_f32_e32 v19, v19, v231
	v_cvt_pk_bf16_f32 v204, v24, v25
	v_cvt_pk_bf16_f32 v205, v26, v27
	v_cvt_pk_bf16_f32 v206, v16, v17
	v_cvt_pk_bf16_f32 v207, v18, v19
	global_store_dwordx4 v[220:221], v[204:207], off
	v_lshl_add_u64 v[220:221], v[220:221], 0, s[88:89]
	v_mul_f32_e32 v224, v12, v246
	v_mul_f32_e32 v225, v13, v246
	v_mul_f32_e32 v226, v14, v246
	v_mul_f32_e32 v227, v15, v246
	v_mul_f32_e32 v228, v4, v246
	v_mul_f32_e32 v229, v5, v246
	v_mul_f32_e32 v230, v6, v246
	v_mul_f32_e32 v231, v7, v246
	v_mul_f32_e32 v8, v12, v8
	v_mul_f32_e32 v9, v13, v9
	v_mul_f32_e32 v10, v14, v10
	v_mul_f32_e32 v11, v15, v11
	v_mul_f32_e32 v0, v4, v0
	v_mul_f32_e32 v1, v5, v1
	v_mul_f32_e32 v2, v6, v2
	v_mul_f32_e32 v3, v7, v3
	v_exp_f32_e32 v224, v224
	v_exp_f32_e32 v225, v225
	v_exp_f32_e32 v226, v226
	v_exp_f32_e32 v227, v227
	v_exp_f32_e32 v228, v228
	v_exp_f32_e32 v229, v229
	v_exp_f32_e32 v230, v230
	v_exp_f32_e32 v231, v231
	v_mul_f32_e32 v8, v8, v247
	v_mul_f32_e32 v9, v9, v247
	v_mul_f32_e32 v10, v10, v247
	v_mul_f32_e32 v11, v11, v247
	v_mul_f32_e32 v0, v0, v247
	v_mul_f32_e32 v1, v1, v247
	v_mul_f32_e32 v2, v2, v247
	v_mul_f32_e32 v3, v3, v247
	v_add_f32_e32 v224, 1.0, v224
	v_add_f32_e32 v225, 1.0, v225
	v_add_f32_e32 v226, 1.0, v226
	v_add_f32_e32 v227, 1.0, v227
	v_add_f32_e32 v228, 1.0, v228
	v_add_f32_e32 v229, 1.0, v229
	v_add_f32_e32 v230, 1.0, v230
	v_add_f32_e32 v231, 1.0, v231
	v_rcp_f32_e32 v224, v224
	v_rcp_f32_e32 v225, v225
	v_rcp_f32_e32 v226, v226
	v_rcp_f32_e32 v227, v227
	v_rcp_f32_e32 v228, v228
	v_rcp_f32_e32 v229, v229
	v_rcp_f32_e32 v230, v230
	v_rcp_f32_e32 v231, v231
	v_mul_f32_e32 v8, v8, v224
	v_mul_f32_e32 v9, v9, v225
	v_mul_f32_e32 v10, v10, v226
	v_mul_f32_e32 v11, v11, v227
	v_mul_f32_e32 v0, v0, v228
	v_mul_f32_e32 v1, v1, v229
	v_mul_f32_e32 v2, v2, v230
	v_mul_f32_e32 v3, v3, v231
	v_cvt_pk_bf16_f32 v208, v8, v9
	v_cvt_pk_bf16_f32 v209, v10, v11
	v_cvt_pk_bf16_f32 v210, v0, v1
	v_cvt_pk_bf16_f32 v211, v2, v3
	global_store_dwordx4 v[220:221], v[208:211], off
	s_andn2_b64 vcc, exec, s[8:9]
	s_mov_b64 s[8:9], -1
	s_cbranch_vccnz .LBB0_615
	s_andn2_b64 vcc, exec, s[14:15]
	s_cbranch_vccnz .LBB0_614
	s_barrier
	s_branch .LBB0_614

.LBB0_1362:
	s_movk_i32 s84, 0x1600
	s_mov_b64 s[88:89], 0x16000
	s_mov_b64 s[90:91], 0x6e000
	v_lshl_add_u32 v178, s51, 12, v168
	ds_read_b128 v[180:183], v178 offset:0
	ds_read_b128 v[184:187], v178 offset:256
	ds_read_b128 v[188:191], v178 offset:512
	ds_read_b128 v[192:195], v178 offset:768
	ds_read_b128 v[196:199], v178 offset:2048
	ds_read_b128 v[200:203], v178 offset:2304
	ds_read_b128 v[204:207], v178 offset:2560
	ds_read_b128 v[208:211], v178 offset:2816
	v_lshl_add_u32 v218, s30, 8, v166
	v_lshl_or_b32 v222, s34, 7, v169
	v_mov_b32_e32 v223, 0
	v_lshlrev_b32_e32 v222, 1, v222
	v_mad_u64_u32 v[220:221], s[82:83], v218, s84, v[142:143]
	v_lshl_add_u64 v[220:221], v[222:223], 0, v[220:221]
	s_waitcnt lgkmcnt(0)
	v_add_f32_e32 v180, v180, v181
	v_add_f32_e32 v184, v184, v185
	v_add_f32_e32 v188, v188, v189
	v_add_f32_e32 v192, v192, v193
	v_add_f32_e32 v196, v196, v197
	v_add_f32_e32 v200, v200, v201
	v_add_f32_e32 v204, v204, v205
	v_add_f32_e32 v208, v208, v209
	v_add_f32_e32 v182, v182, v183
	v_add_f32_e32 v186, v186, v187
	v_add_f32_e32 v190, v190, v191
	v_add_f32_e32 v194, v194, v195
	v_add_f32_e32 v198, v198, v199
	v_add_f32_e32 v202, v202, v203
	v_add_f32_e32 v206, v206, v207
	v_add_f32_e32 v210, v210, v211
	v_add_f32_e32 v180, v180, v182
	v_add_f32_e32 v184, v184, v186
	v_add_f32_e32 v188, v188, v190
	v_add_f32_e32 v192, v192, v194
	v_add_f32_e32 v196, v196, v198
	v_add_f32_e32 v200, v200, v202
	v_add_f32_e32 v204, v204, v206
	v_add_f32_e32 v208, v208, v210
	v_fmamk_f32 v180, v180, 0x3a800000, v171
	v_fmamk_f32 v184, v184, 0x3a800000, v171
	v_fmamk_f32 v188, v188, 0x3a800000, v171
	v_fmamk_f32 v192, v192, 0x3a800000, v171
	v_fmamk_f32 v196, v196, 0x3a800000, v171
	v_fmamk_f32 v200, v200, 0x3a800000, v171
	v_fmamk_f32 v204, v204, 0x3a800000, v171
	v_fmamk_f32 v208, v208, 0x3a800000, v171
	v_rsq_f32_e32 v180, v180
	v_rsq_f32_e32 v184, v184
	v_rsq_f32_e32 v188, v188
	v_rsq_f32_e32 v192, v192
	v_rsq_f32_e32 v196, v196
	v_rsq_f32_e32 v200, v200
	v_rsq_f32_e32 v204, v204
	v_rsq_f32_e32 v208, v208
	v_mul_f32_e32 v232, 0xbfb8aa3b, v180
	v_mul_f32_e32 v234, 0xbfb8aa3b, v184
	v_mul_f32_e32 v236, 0xbfb8aa3b, v188
	v_mul_f32_e32 v238, 0xbfb8aa3b, v192
	v_mul_f32_e32 v240, 0xbfb8aa3b, v196
	v_mul_f32_e32 v242, 0xbfb8aa3b, v200
	v_mul_f32_e32 v244, 0xbfb8aa3b, v204
	v_mul_f32_e32 v246, 0xbfb8aa3b, v208
	v_mul_f32_e32 v233, v180, v180
	v_mul_f32_e32 v235, v184, v184
	v_mul_f32_e32 v237, v188, v188
	v_mul_f32_e32 v239, v192, v192
	v_mul_f32_e32 v241, v196, v196
	v_mul_f32_e32 v243, v200, v200
	v_mul_f32_e32 v245, v204, v204
	v_mul_f32_e32 v247, v208, v208
	v_mul_f32_e32 v224, v124, v232
	v_mul_f32_e32 v225, v125, v232
	v_mul_f32_e32 v226, v126, v232
	v_mul_f32_e32 v227, v127, v232
	v_mul_f32_e32 v228, v116, v232
	v_mul_f32_e32 v229, v117, v232
	v_mul_f32_e32 v230, v118, v232
	v_mul_f32_e32 v231, v119, v232
	v_mul_f32_e32 v120, v124, v120
	v_mul_f32_e32 v121, v125, v121
	v_mul_f32_e32 v122, v126, v122
	v_mul_f32_e32 v123, v127, v123
	v_mul_f32_e32 v112, v116, v112
	v_mul_f32_e32 v113, v117, v113
	v_mul_f32_e32 v114, v118, v114
	v_mul_f32_e32 v115, v119, v115
	v_exp_f32_e32 v224, v224
	v_exp_f32_e32 v225, v225
	v_exp_f32_e32 v226, v226
	v_exp_f32_e32 v227, v227
	v_exp_f32_e32 v228, v228
	v_exp_f32_e32 v229, v229
	v_exp_f32_e32 v230, v230
	v_exp_f32_e32 v231, v231
	v_mul_f32_e32 v120, v120, v233
	v_mul_f32_e32 v121, v121, v233
	v_mul_f32_e32 v122, v122, v233
	v_mul_f32_e32 v123, v123, v233
	v_mul_f32_e32 v112, v112, v233
	v_mul_f32_e32 v113, v113, v233
	v_mul_f32_e32 v114, v114, v233
	v_mul_f32_e32 v115, v115, v233
	v_add_f32_e32 v224, 1.0, v224
	v_add_f32_e32 v225, 1.0, v225
	v_add_f32_e32 v226, 1.0, v226
	v_add_f32_e32 v227, 1.0, v227
	v_add_f32_e32 v228, 1.0, v228
	v_add_f32_e32 v229, 1.0, v229
	v_add_f32_e32 v230, 1.0, v230
	v_add_f32_e32 v231, 1.0, v231
	v_rcp_f32_e32 v224, v224
	v_rcp_f32_e32 v225, v225
	v_rcp_f32_e32 v226, v226
	v_rcp_f32_e32 v227, v227
	v_rcp_f32_e32 v228, v228
	v_rcp_f32_e32 v229, v229
	v_rcp_f32_e32 v230, v230
	v_rcp_f32_e32 v231, v231
	v_mul_f32_e32 v120, v120, v224
	v_mul_f32_e32 v121, v121, v225
	v_mul_f32_e32 v122, v122, v226
	v_mul_f32_e32 v123, v123, v227
	v_mul_f32_e32 v112, v112, v228
	v_mul_f32_e32 v113, v113, v229
	v_mul_f32_e32 v114, v114, v230
	v_mul_f32_e32 v115, v115, v231
	v_cvt_pk_bf16_f32 v180, v120, v121
	v_cvt_pk_bf16_f32 v181, v122, v123
	v_cvt_pk_bf16_f32 v182, v112, v113
	v_cvt_pk_bf16_f32 v183, v114, v115
	global_store_dwordx4 v[220:221], v[180:183], off
	v_lshl_add_u64 v[220:221], v[220:221], 0, s[88:89]
	v_mul_f32_e32 v224, v108, v234
	v_mul_f32_e32 v225, v109, v234
	v_mul_f32_e32 v226, v110, v234
	v_mul_f32_e32 v227, v111, v234
	v_mul_f32_e32 v228, v100, v234
	v_mul_f32_e32 v229, v101, v234
	v_mul_f32_e32 v230, v102, v234
	v_mul_f32_e32 v231, v103, v234
	v_mul_f32_e32 v104, v108, v104
	v_mul_f32_e32 v105, v109, v105
	v_mul_f32_e32 v106, v110, v106
	v_mul_f32_e32 v107, v111, v107
	v_mul_f32_e32 v96, v100, v96
	v_mul_f32_e32 v97, v101, v97
	v_mul_f32_e32 v98, v102, v98
	v_mul_f32_e32 v99, v103, v99
	v_exp_f32_e32 v224, v224
	v_exp_f32_e32 v225, v225
	v_exp_f32_e32 v226, v226
	v_exp_f32_e32 v227, v227
	v_exp_f32_e32 v228, v228
	v_exp_f32_e32 v229, v229
	v_exp_f32_e32 v230, v230
	v_exp_f32_e32 v231, v231
	v_mul_f32_e32 v104, v104, v235
	v_mul_f32_e32 v105, v105, v235
	v_mul_f32_e32 v106, v106, v235
	v_mul_f32_e32 v107, v107, v235
	v_mul_f32_e32 v96, v96, v235
	v_mul_f32_e32 v97, v97, v235
	v_mul_f32_e32 v98, v98, v235
	v_mul_f32_e32 v99, v99, v235
	v_add_f32_e32 v224, 1.0, v224
	v_add_f32_e32 v225, 1.0, v225
	v_add_f32_e32 v226, 1.0, v226
	v_add_f32_e32 v227, 1.0, v227
	v_add_f32_e32 v228, 1.0, v228
	v_add_f32_e32 v229, 1.0, v229
	v_add_f32_e32 v230, 1.0, v230
	v_add_f32_e32 v231, 1.0, v231
	v_rcp_f32_e32 v224, v224
	v_rcp_f32_e32 v225, v225
	v_rcp_f32_e32 v226, v226
	v_rcp_f32_e32 v227, v227
	v_rcp_f32_e32 v228, v228
	v_rcp_f32_e32 v229, v229
	v_rcp_f32_e32 v230, v230
	v_rcp_f32_e32 v231, v231
	v_mul_f32_e32 v104, v104, v224
	v_mul_f32_e32 v105, v105, v225
	v_mul_f32_e32 v106, v106, v226
	v_mul_f32_e32 v107, v107, v227
	v_mul_f32_e32 v96, v96, v228
	v_mul_f32_e32 v97, v97, v229
	v_mul_f32_e32 v98, v98, v230
	v_mul_f32_e32 v99, v99, v231
	v_cvt_pk_bf16_f32 v184, v104, v105
	v_cvt_pk_bf16_f32 v185, v106, v107
	v_cvt_pk_bf16_f32 v186, v96, v97
	v_cvt_pk_bf16_f32 v187, v98, v99
	global_store_dwordx4 v[220:221], v[184:187], off
	v_lshl_add_u64 v[220:221], v[220:221], 0, s[88:89]
	v_mul_f32_e32 v224, v92, v236
	v_mul_f32_e32 v225, v93, v236
	v_mul_f32_e32 v226, v94, v236
	v_mul_f32_e32 v227, v95, v236
	v_mul_f32_e32 v228, v84, v236
	v_mul_f32_e32 v229, v85, v236
	v_mul_f32_e32 v230, v86, v236
	v_mul_f32_e32 v231, v87, v236
	v_mul_f32_e32 v88, v92, v88
	v_mul_f32_e32 v89, v93, v89
	v_mul_f32_e32 v90, v94, v90
	v_mul_f32_e32 v91, v95, v91
	v_mul_f32_e32 v80, v84, v80
	v_mul_f32_e32 v81, v85, v81
	v_mul_f32_e32 v82, v86, v82
	v_mul_f32_e32 v83, v87, v83
	v_exp_f32_e32 v224, v224
	v_exp_f32_e32 v225, v225
	v_exp_f32_e32 v226, v226
	v_exp_f32_e32 v227, v227
	v_exp_f32_e32 v228, v228
	v_exp_f32_e32 v229, v229
	v_exp_f32_e32 v230, v230
	v_exp_f32_e32 v231, v231
	v_mul_f32_e32 v88, v88, v237
	v_mul_f32_e32 v89, v89, v237
	v_mul_f32_e32 v90, v90, v237
	v_mul_f32_e32 v91, v91, v237
	v_mul_f32_e32 v80, v80, v237
	v_mul_f32_e32 v81, v81, v237
	v_mul_f32_e32 v82, v82, v237
	v_mul_f32_e32 v83, v83, v237
	v_add_f32_e32 v224, 1.0, v224
	v_add_f32_e32 v225, 1.0, v225
	v_add_f32_e32 v226, 1.0, v226
	v_add_f32_e32 v227, 1.0, v227
	v_add_f32_e32 v228, 1.0, v228
	v_add_f32_e32 v229, 1.0, v229
	v_add_f32_e32 v230, 1.0, v230
	v_add_f32_e32 v231, 1.0, v231
	v_rcp_f32_e32 v224, v224
	v_rcp_f32_e32 v225, v225
	v_rcp_f32_e32 v226, v226
	v_rcp_f32_e32 v227, v227
	v_rcp_f32_e32 v228, v228
	v_rcp_f32_e32 v229, v229
	v_rcp_f32_e32 v230, v230
	v_rcp_f32_e32 v231, v231
	v_mul_f32_e32 v88, v88, v224
	v_mul_f32_e32 v89, v89, v225
	v_mul_f32_e32 v90, v90, v226
	v_mul_f32_e32 v91, v91, v227
	v_mul_f32_e32 v80, v80, v228
	v_mul_f32_e32 v81, v81, v229
	v_mul_f32_e32 v82, v82, v230
	v_mul_f32_e32 v83, v83, v231
	v_cvt_pk_bf16_f32 v188, v88, v89
	v_cvt_pk_bf16_f32 v189, v90, v91
	v_cvt_pk_bf16_f32 v190, v80, v81
	v_cvt_pk_bf16_f32 v191, v82, v83
	global_store_dwordx4 v[220:221], v[188:191], off
	v_lshl_add_u64 v[220:221], v[220:221], 0, s[88:89]
	v_mul_f32_e32 v224, v76, v238
	v_mul_f32_e32 v225, v77, v238
	v_mul_f32_e32 v226, v78, v238
	v_mul_f32_e32 v227, v79, v238
	v_mul_f32_e32 v228, v68, v238
	v_mul_f32_e32 v229, v69, v238
	v_mul_f32_e32 v230, v70, v238
	v_mul_f32_e32 v231, v71, v238
	v_mul_f32_e32 v72, v76, v72
	v_mul_f32_e32 v73, v77, v73
	v_mul_f32_e32 v74, v78, v74
	v_mul_f32_e32 v75, v79, v75
	v_mul_f32_e32 v64, v68, v64
	v_mul_f32_e32 v65, v69, v65
	v_mul_f32_e32 v66, v70, v66
	v_mul_f32_e32 v67, v71, v67
	v_exp_f32_e32 v224, v224
	v_exp_f32_e32 v225, v225
	v_exp_f32_e32 v226, v226
	v_exp_f32_e32 v227, v227
	v_exp_f32_e32 v228, v228
	v_exp_f32_e32 v229, v229
	v_exp_f32_e32 v230, v230
	v_exp_f32_e32 v231, v231
	v_mul_f32_e32 v72, v72, v239
	v_mul_f32_e32 v73, v73, v239
	v_mul_f32_e32 v74, v74, v239
	v_mul_f32_e32 v75, v75, v239
	v_mul_f32_e32 v64, v64, v239
	v_mul_f32_e32 v65, v65, v239
	v_mul_f32_e32 v66, v66, v239
	v_mul_f32_e32 v67, v67, v239
	v_add_f32_e32 v224, 1.0, v224
	v_add_f32_e32 v225, 1.0, v225
	v_add_f32_e32 v226, 1.0, v226
	v_add_f32_e32 v227, 1.0, v227
	v_add_f32_e32 v228, 1.0, v228
	v_add_f32_e32 v229, 1.0, v229
	v_add_f32_e32 v230, 1.0, v230
	v_add_f32_e32 v231, 1.0, v231
	v_rcp_f32_e32 v224, v224
	v_rcp_f32_e32 v225, v225
	v_rcp_f32_e32 v226, v226
	v_rcp_f32_e32 v227, v227
	v_rcp_f32_e32 v228, v228
	v_rcp_f32_e32 v229, v229
	v_rcp_f32_e32 v230, v230
	v_rcp_f32_e32 v231, v231
	v_mul_f32_e32 v72, v72, v224
	v_mul_f32_e32 v73, v73, v225
	v_mul_f32_e32 v74, v74, v226
	v_mul_f32_e32 v75, v75, v227
	v_mul_f32_e32 v64, v64, v228
	v_mul_f32_e32 v65, v65, v229
	v_mul_f32_e32 v66, v66, v230
	v_mul_f32_e32 v67, v67, v231
	v_cvt_pk_bf16_f32 v192, v72, v73
	v_cvt_pk_bf16_f32 v193, v74, v75
	v_cvt_pk_bf16_f32 v194, v64, v65
	v_cvt_pk_bf16_f32 v195, v66, v67
	global_store_dwordx4 v[220:221], v[192:195], off
	v_lshl_add_u64 v[220:221], v[220:221], 0, s[90:91]
	v_mul_f32_e32 v224, v60, v240
	v_mul_f32_e32 v225, v61, v240
	v_mul_f32_e32 v226, v62, v240
	v_mul_f32_e32 v227, v63, v240
	v_mul_f32_e32 v228, v52, v240
	v_mul_f32_e32 v229, v53, v240
	v_mul_f32_e32 v230, v54, v240
	v_mul_f32_e32 v231, v55, v240
	v_mul_f32_e32 v56, v60, v56
	v_mul_f32_e32 v57, v61, v57
	v_mul_f32_e32 v58, v62, v58
	v_mul_f32_e32 v59, v63, v59
	v_mul_f32_e32 v48, v52, v48
	v_mul_f32_e32 v49, v53, v49
	v_mul_f32_e32 v50, v54, v50
	v_mul_f32_e32 v51, v55, v51
	v_exp_f32_e32 v224, v224
	v_exp_f32_e32 v225, v225
	v_exp_f32_e32 v226, v226
	v_exp_f32_e32 v227, v227
	v_exp_f32_e32 v228, v228
	v_exp_f32_e32 v229, v229
	v_exp_f32_e32 v230, v230
	v_exp_f32_e32 v231, v231
	v_mul_f32_e32 v56, v56, v241
	v_mul_f32_e32 v57, v57, v241
	v_mul_f32_e32 v58, v58, v241
	v_mul_f32_e32 v59, v59, v241
	v_mul_f32_e32 v48, v48, v241
	v_mul_f32_e32 v49, v49, v241
	v_mul_f32_e32 v50, v50, v241
	v_mul_f32_e32 v51, v51, v241
	v_add_f32_e32 v224, 1.0, v224
	v_add_f32_e32 v225, 1.0, v225
	v_add_f32_e32 v226, 1.0, v226
	v_add_f32_e32 v227, 1.0, v227
	v_add_f32_e32 v228, 1.0, v228
	v_add_f32_e32 v229, 1.0, v229
	v_add_f32_e32 v230, 1.0, v230
	v_add_f32_e32 v231, 1.0, v231
	v_rcp_f32_e32 v224, v224
	v_rcp_f32_e32 v225, v225
	v_rcp_f32_e32 v226, v226
	v_rcp_f32_e32 v227, v227
	v_rcp_f32_e32 v228, v228
	v_rcp_f32_e32 v229, v229
	v_rcp_f32_e32 v230, v230
	v_rcp_f32_e32 v231, v231
	v_mul_f32_e32 v56, v56, v224
	v_mul_f32_e32 v57, v57, v225
	v_mul_f32_e32 v58, v58, v226
	v_mul_f32_e32 v59, v59, v227
	v_mul_f32_e32 v48, v48, v228
	v_mul_f32_e32 v49, v49, v229
	v_mul_f32_e32 v50, v50, v230
	v_mul_f32_e32 v51, v51, v231
	v_cvt_pk_bf16_f32 v196, v56, v57
	v_cvt_pk_bf16_f32 v197, v58, v59
	v_cvt_pk_bf16_f32 v198, v48, v49
	v_cvt_pk_bf16_f32 v199, v50, v51
	global_store_dwordx4 v[220:221], v[196:199], off
	v_lshl_add_u64 v[220:221], v[220:221], 0, s[88:89]
	v_mul_f32_e32 v224, v44, v242
	v_mul_f32_e32 v225, v45, v242
	v_mul_f32_e32 v226, v46, v242
	v_mul_f32_e32 v227, v47, v242
	v_mul_f32_e32 v228, v36, v242
	v_mul_f32_e32 v229, v37, v242
	v_mul_f32_e32 v230, v38, v242
	v_mul_f32_e32 v231, v39, v242
	v_mul_f32_e32 v40, v44, v40
	v_mul_f32_e32 v41, v45, v41
	v_mul_f32_e32 v42, v46, v42
	v_mul_f32_e32 v43, v47, v43
	v_mul_f32_e32 v32, v36, v32
	v_mul_f32_e32 v33, v37, v33
	v_mul_f32_e32 v34, v38, v34
	v_mul_f32_e32 v35, v39, v35
	v_exp_f32_e32 v224, v224
	v_exp_f32_e32 v225, v225
	v_exp_f32_e32 v226, v226
	v_exp_f32_e32 v227, v227
	v_exp_f32_e32 v228, v228
	v_exp_f32_e32 v229, v229
	v_exp_f32_e32 v230, v230
	v_exp_f32_e32 v231, v231
	v_mul_f32_e32 v40, v40, v243
	v_mul_f32_e32 v41, v41, v243
	v_mul_f32_e32 v42, v42, v243
	v_mul_f32_e32 v43, v43, v243
	v_mul_f32_e32 v32, v32, v243
	v_mul_f32_e32 v33, v33, v243
	v_mul_f32_e32 v34, v34, v243
	v_mul_f32_e32 v35, v35, v243
	v_add_f32_e32 v224, 1.0, v224
	v_add_f32_e32 v225, 1.0, v225
	v_add_f32_e32 v226, 1.0, v226
	v_add_f32_e32 v227, 1.0, v227
	v_add_f32_e32 v228, 1.0, v228
	v_add_f32_e32 v229, 1.0, v229
	v_add_f32_e32 v230, 1.0, v230
	v_add_f32_e32 v231, 1.0, v231
	v_rcp_f32_e32 v224, v224
	v_rcp_f32_e32 v225, v225
	v_rcp_f32_e32 v226, v226
	v_rcp_f32_e32 v227, v227
	v_rcp_f32_e32 v228, v228
	v_rcp_f32_e32 v229, v229
	v_rcp_f32_e32 v230, v230
	v_rcp_f32_e32 v231, v231
	v_mul_f32_e32 v40, v40, v224
	v_mul_f32_e32 v41, v41, v225
	v_mul_f32_e32 v42, v42, v226
	v_mul_f32_e32 v43, v43, v227
	v_mul_f32_e32 v32, v32, v228
	v_mul_f32_e32 v33, v33, v229
	v_mul_f32_e32 v34, v34, v230
	v_mul_f32_e32 v35, v35, v231
	v_cvt_pk_bf16_f32 v200, v40, v41
	v_cvt_pk_bf16_f32 v201, v42, v43
	v_cvt_pk_bf16_f32 v202, v32, v33
	v_cvt_pk_bf16_f32 v203, v34, v35
	global_store_dwordx4 v[220:221], v[200:203], off
	v_lshl_add_u64 v[220:221], v[220:221], 0, s[88:89]
	v_mul_f32_e32 v224, v28, v244
	v_mul_f32_e32 v225, v29, v244
	v_mul_f32_e32 v226, v30, v244
	v_mul_f32_e32 v227, v31, v244
	v_mul_f32_e32 v228, v20, v244
	v_mul_f32_e32 v229, v21, v244
	v_mul_f32_e32 v230, v22, v244
	v_mul_f32_e32 v231, v23, v244
	v_mul_f32_e32 v24, v28, v24
	v_mul_f32_e32 v25, v29, v25
	v_mul_f32_e32 v26, v30, v26
	v_mul_f32_e32 v27, v31, v27
	v_mul_f32_e32 v16, v20, v16
	v_mul_f32_e32 v17, v21, v17
	v_mul_f32_e32 v18, v22, v18
	v_mul_f32_e32 v19, v23, v19
	v_exp_f32_e32 v224, v224
	v_exp_f32_e32 v225, v225
	v_exp_f32_e32 v226, v226
	v_exp_f32_e32 v227, v227
	v_exp_f32_e32 v228, v228
	v_exp_f32_e32 v229, v229
	v_exp_f32_e32 v230, v230
	v_exp_f32_e32 v231, v231
	v_mul_f32_e32 v24, v24, v245
	v_mul_f32_e32 v25, v25, v245
	v_mul_f32_e32 v26, v26, v245
	v_mul_f32_e32 v27, v27, v245
	v_mul_f32_e32 v16, v16, v245
	v_mul_f32_e32 v17, v17, v245
	v_mul_f32_e32 v18, v18, v245
	v_mul_f32_e32 v19, v19, v245
	v_add_f32_e32 v224, 1.0, v224
	v_add_f32_e32 v225, 1.0, v225
	v_add_f32_e32 v226, 1.0, v226
	v_add_f32_e32 v227, 1.0, v227
	v_add_f32_e32 v228, 1.0, v228
	v_add_f32_e32 v229, 1.0, v229
	v_add_f32_e32 v230, 1.0, v230
	v_add_f32_e32 v231, 1.0, v231
	v_rcp_f32_e32 v224, v224
	v_rcp_f32_e32 v225, v225
	v_rcp_f32_e32 v226, v226
	v_rcp_f32_e32 v227, v227
	v_rcp_f32_e32 v228, v228
	v_rcp_f32_e32 v229, v229
	v_rcp_f32_e32 v230, v230
	v_rcp_f32_e32 v231, v231
	v_mul_f32_e32 v24, v24, v224
	v_mul_f32_e32 v25, v25, v225
	v_mul_f32_e32 v26, v26, v226
	v_mul_f32_e32 v27, v27, v227
	v_mul_f32_e32 v16, v16, v228
	v_mul_f32_e32 v17, v17, v229
	v_mul_f32_e32 v18, v18, v230
	v_mul_f32_e32 v19, v19, v231
	v_cvt_pk_bf16_f32 v204, v24, v25
	v_cvt_pk_bf16_f32 v205, v26, v27
	v_cvt_pk_bf16_f32 v206, v16, v17
	v_cvt_pk_bf16_f32 v207, v18, v19
	global_store_dwordx4 v[220:221], v[204:207], off
	v_lshl_add_u64 v[220:221], v[220:221], 0, s[88:89]
	v_mul_f32_e32 v224, v12, v246
	v_mul_f32_e32 v225, v13, v246
	v_mul_f32_e32 v226, v14, v246
	v_mul_f32_e32 v227, v15, v246
	v_mul_f32_e32 v228, v4, v246
	v_mul_f32_e32 v229, v5, v246
	v_mul_f32_e32 v230, v6, v246
	v_mul_f32_e32 v231, v7, v246
	v_mul_f32_e32 v8, v12, v8
	v_mul_f32_e32 v9, v13, v9
	v_mul_f32_e32 v10, v14, v10
	v_mul_f32_e32 v11, v15, v11
	v_mul_f32_e32 v0, v4, v0
	v_mul_f32_e32 v1, v5, v1
	v_mul_f32_e32 v2, v6, v2
	v_mul_f32_e32 v3, v7, v3
	v_exp_f32_e32 v224, v224
	v_exp_f32_e32 v225, v225
	v_exp_f32_e32 v226, v226
	v_exp_f32_e32 v227, v227
	v_exp_f32_e32 v228, v228
	v_exp_f32_e32 v229, v229
	v_exp_f32_e32 v230, v230
	v_exp_f32_e32 v231, v231
	v_mul_f32_e32 v8, v8, v247
	v_mul_f32_e32 v9, v9, v247
	v_mul_f32_e32 v10, v10, v247
	v_mul_f32_e32 v11, v11, v247
	v_mul_f32_e32 v0, v0, v247
	v_mul_f32_e32 v1, v1, v247
	v_mul_f32_e32 v2, v2, v247
	v_mul_f32_e32 v3, v3, v247
	v_add_f32_e32 v224, 1.0, v224
	v_add_f32_e32 v225, 1.0, v225
	v_add_f32_e32 v226, 1.0, v226
	v_add_f32_e32 v227, 1.0, v227
	v_add_f32_e32 v228, 1.0, v228
	v_add_f32_e32 v229, 1.0, v229
	v_add_f32_e32 v230, 1.0, v230
	v_add_f32_e32 v231, 1.0, v231
	v_rcp_f32_e32 v224, v224
	v_rcp_f32_e32 v225, v225
	v_rcp_f32_e32 v226, v226
	v_rcp_f32_e32 v227, v227
	v_rcp_f32_e32 v228, v228
	v_rcp_f32_e32 v229, v229
	v_rcp_f32_e32 v230, v230
	v_rcp_f32_e32 v231, v231
	v_mul_f32_e32 v8, v8, v224
	v_mul_f32_e32 v9, v9, v225
	v_mul_f32_e32 v10, v10, v226
	v_mul_f32_e32 v11, v11, v227
	v_mul_f32_e32 v0, v0, v228
	v_mul_f32_e32 v1, v1, v229
	v_mul_f32_e32 v2, v2, v230
	v_mul_f32_e32 v3, v3, v231
	v_cvt_pk_bf16_f32 v208, v8, v9
	v_cvt_pk_bf16_f32 v209, v10, v11
	v_cvt_pk_bf16_f32 v210, v0, v1
	v_cvt_pk_bf16_f32 v211, v2, v3
	global_store_dwordx4 v[220:221], v[208:211], off
	s_andn2_b64 vcc, exec, s[6:7]
	s_mov_b64 s[6:7], -1
	s_cbranch_vccnz .LBB0_1352
	s_andn2_b64 vcc, exec, s[12:13]
	s_cbranch_vccnz .LBB0_1351
	s_barrier
	s_branch .LBB0_1351
